# barrier: after the arrive atomic wait vmcnt(1) (atomic result only) so the early invalidate completes in the background
# baseline (speedup 1.0000x reference)
; __device__ __forceinline__ unsigned xb_ld(unsigned* p)              { return __hip_atomic_load(p, __ATOMIC_RELAXED, __HIP_MEMORY_SCOPE_AGENT); }
; __device__ __forceinline__ unsigned xb_add(unsigned* p, unsigned v) { return __hip_atomic_fetch_add(p, v, __ATOMIC_RELAXED, __HIP_MEMORY_SCOPE_AGENT); }
; #define XB_SPIN(cond, bar) do { unsigned _sp = 0; while (cond) { __builtin_amdgcn_s_sleep(1); \
;     if ((++_sp & 255u) == 0u) { if (xb_ld(&(bar)[XB_TMO])) break; if (_sp > XB_SPIN_CAP) { atomicAdd(&(bar)[XB_TMO], 1u); break; } } } } while (0)
; __device__ __forceinline__ void xcd_barrier(const XcdBarrier& b, const int tid) {
;     ...
;         const unsigned old = xb_add(&bar[XB_XSUB(b.x)], 1u);
;         const unsigned gen = old / nloc;
;         if (old + 1u == (gen + 1u) * nloc) {
;             __builtin_amdgcn_fence(__ATOMIC_RELEASE, "agent");
;             asm volatile("s_waitcnt vmcnt(0)" ::: "memory");
;             const unsigned og = xb_add(&bar[XB_TOP], 1u);
;             const unsigned tg = og / nx;
;             if (og + 1u == (tg + 1u) * nx) xb_add(&bar[XB_TOPGEN], 1u);
;             else XB_SPIN(xb_ld(&bar[XB_TOPGEN]) == tg, bar);
.LBB0_40:
	s_or_b64 exec, exec, s[6:7]
	buffer_inv sc1
	v_cvt_f32_u32_e32 v5, v3
	s_waitcnt vmcnt(1)
	v_readfirstlane_b32 s4, v4
	v_sub_u32_e32 v4, 0, v3
	v_rcp_iflag_f32_e32 v5, v5
	v_add_u32_e32 v6, s4, v1
	v_mul_f32_e32 v5, 0x4f7ffffe, v5
	v_cvt_u32_f32_e32 v5, v5
	v_mul_lo_u32 v1, v4, v5
	v_mul_hi_u32 v1, v5, v1
	v_add_u32_e32 v1, v5, v1
	v_mul_hi_u32 v1, v6, v1
	v_mul_lo_u32 v4, v1, v3
	v_sub_u32_e32 v4, v6, v4
	v_add_u32_e32 v5, 1, v1
	v_cmp_ge_u32_e32 vcc, v4, v3
	s_nop 1
	v_cndmask_b32_e32 v1, v1, v5, vcc
	v_sub_u32_e32 v5, v4, v3
	v_cndmask_b32_e32 v4, v4, v5, vcc
	v_add_u32_e32 v5, 1, v1
	v_cmp_ge_u32_e32 vcc, v4, v3
	v_add_u32_e32 v4, 1, v6
	s_nop 0
	v_cndmask_b32_e32 v1, v1, v5, vcc
	v_mul_lo_u32 v5, v3, v1
	v_add_u32_e32 v3, v5, v3
	v_cmp_ne_u32_e32 vcc, v4, v3
	s_and_saveexec_b64 s[4:5], vcc
	s_xor_b64 s[4:5], exec, s[4:5]
	s_cbranch_execz .LBB0_54
	s_waitcnt lgkmcnt(0)
	s_add_u32 s10, s22, 0x11d03500
	s_addc_u32 s11, s23, 0
	global_load_dword v2, v179, s[10:11] sc1
	s_nop 0
	s_waitcnt vmcnt(0)
	v_cmp_eq_u32_e32 vcc, v2, v1
	s_and_saveexec_b64 s[6:7], vcc
	s_cbranch_execz .LBB0_53
	s_add_u32 s8, s22, 0x11d00200
	s_addc_u32 s9, s23, 0
	s_mov_b32 s24, 1
	s_mov_b64 s[12:13], 0
	s_branch .LBB0_44
